# P3: latent tiles whose other 16-key half is masked for the whole wave skip that half's exp/sum/PV (values unchanged); on top of v108
# baseline (speedup 1.0000x reference)
.Lp3_m0join:
	ds_read_b128 v[198:201], v188 offset:32768
	ds_read_b64_tr_b16 v[134:135], v182
	ds_read_b64_tr_b16 v[118:119], v182 offset:4096
	s_waitcnt lgkmcnt(11)
	v_mfma_f32_32x32x16_bf16 v[66:81], v[202:205], v[86:89], v[66:81]
	ds_read_b128 v[202:205], v189 offset:32768
	ds_read_b64_tr_b16 v[130:131], v183
	ds_read_b64_tr_b16 v[114:115], v183 offset:4096
	s_waitcnt lgkmcnt(13)
	v_mfma_f32_32x32x16_bf16 v[66:81], v[206:209], v[90:93], v[66:81]
	ds_read_b64_tr_b16 v[144:145], v184
	ds_read_b64_tr_b16 v[128:129], v184 offset:4096
	s_waitcnt lgkmcnt(13)
	v_mfma_f32_32x32x16_bf16 v[66:81], v[210:213], v[94:97], v[66:81]
	ds_read_b64_tr_b16 v[140:141], v185
	ds_read_b64_tr_b16 v[124:125], v185 offset:4096
	s_waitcnt lgkmcnt(13)
	v_mfma_f32_32x32x16_bf16 v[66:81], v[214:217], v[98:101], v[66:81]
	ds_read_b64_tr_b16 v[136:137], v186
	ds_read_b64_tr_b16 v[120:121], v186 offset:4096
	s_waitcnt lgkmcnt(13)
	v_mfma_f32_32x32x16_bf16 v[66:81], v[218:221], v[102:105], v[66:81]
	ds_read_b64_tr_b16 v[132:133], v187
	ds_read_b64_tr_b16 v[116:117], v187 offset:4096
	s_cbranch_vccnz .Lp3_ctx67
	s_sub_i32 s18, s79, s0
	s_and_b32 s19, s75, 32
	s_mulk_i32 s18, 0x7c
	s_lshl_b32 s33, s19, 2
	s_add_i32 s33, s33, s18
	s_addk_i32 s33, 0x7a0
	v_add_u32_e32 v188, s33, v176
	s_waitcnt lgkmcnt(7)
	ds_read2_b32 v[180:181], v188 offset1:1
	ds_read2_b32 v[182:183], v188 offset0:2 offset1:3
	ds_read2_b32 v[184:185], v188 offset0:4 offset1:5
	ds_read2_b32 v[186:187], v188 offset0:6 offset1:7
	ds_read2_b32 v[190:191], v188 offset0:16 offset1:17
	ds_read2_b32 v[192:193], v188 offset0:18 offset1:19
	ds_read2_b32 v[194:195], v188 offset0:20 offset1:21
	ds_read2_b32 v[188:189], v188 offset0:22 offset1:23
	v_mfma_f32_32x32x16_bf16 v[66:81], v[198:201], v[106:109], v[66:81]
	v_mfma_f32_32x32x16_bf16 v[66:81], v[202:205], v[110:113], v[66:81]
	s_waitcnt lgkmcnt(0)
	s_nop 10
	v_pk_add_f32 v[66:67], v[66:67], v[180:181]
	v_pk_add_f32 v[68:69], v[68:69], v[182:183]
	v_pk_add_f32 v[70:71], v[70:71], v[184:185]
	v_pk_add_f32 v[72:73], v[72:73], v[186:187]
	v_pk_add_f32 v[74:75], v[74:75], v[190:191]
	v_pk_add_f32 v[76:77], v[76:77], v[192:193]
	v_pk_add_f32 v[78:79], v[78:79], v[194:195]
	v_pk_add_f32 v[80:81], v[80:81], v[188:189]
	s_lshr_b32 s18, s75, 5
	s_xor_b32 s18, s18, s92
	s_bitcmp1_b32 s18, 0
	s_cbranch_scc0 .Lp3_sm
	s_bitcmp1_b32 s92, 0
	s_cbranch_scc1 .Lp3_sp1
	s_branch .Lp3_sp0

.LBB0_544:
	v_sub_f32_e32 v66, v66, v177
	v_exp_f32_e32 v179, v66
	v_sub_f32_e32 v66, v67, v177
	v_exp_f32_e32 v180, v66
	v_sub_f32_e32 v66, v68, v177
	v_exp_f32_e32 v181, v66
	v_sub_f32_e32 v66, v69, v177
	v_exp_f32_e32 v182, v66
	v_sub_f32_e32 v66, v70, v177
	v_exp_f32_e32 v70, v66
	v_sub_f32_e32 v66, v71, v177
	v_exp_f32_e32 v71, v66
	v_sub_f32_e32 v66, v72, v177
	v_exp_f32_e32 v72, v66
	v_sub_f32_e32 v66, v73, v177
	v_exp_f32_e32 v73, v66
	v_cvt_pk_bf16_f32 v66, v179, v180
	v_cvt_pk_bf16_f32 v67, v181, v182
	v_cvt_pk_bf16_f32 v68, v70, v71
	v_cvt_pk_bf16_f32 v69, v72, v73
	s_waitcnt lgkmcnt(0)
	v_sub_f32_e32 v74, v74, v177
	v_sub_f32_e32 v75, v75, v177
	v_mfma_f32_32x32x16_bf16 v[50:65], v[142:145], v[66:69], v[50:65]
	v_sub_f32_e32 v76, v76, v177
	v_sub_f32_e32 v77, v77, v177
	v_sub_f32_e32 v78, v78, v177
	v_sub_f32_e32 v79, v79, v177
	v_sub_f32_e32 v80, v80, v177
	v_exp_f32_e32 v74, v74
	v_exp_f32_e32 v75, v75
	v_mfma_f32_32x32x16_bf16 v[34:49], v[138:141], v[66:69], v[34:49]
	v_exp_f32_e32 v76, v76
	v_exp_f32_e32 v77, v77
	v_exp_f32_e32 v78, v78
	v_exp_f32_e32 v79, v79
	v_exp_f32_e32 v80, v80
	v_mfma_f32_32x32x16_bf16 v[18:33], v[134:137], v[66:69], v[18:33]
	v_mfma_f32_32x32x16_bf16 v[2:17], v[130:133], v[66:69], v[2:17]
	v_sub_f32_e32 v66, v81, v177
	v_exp_f32_e32 v81, v66
	v_cvt_pk_bf16_f32 v66, v74, v75
	v_cvt_pk_bf16_f32 v67, v76, v77
	v_cvt_pk_bf16_f32 v68, v78, v79
	v_cvt_pk_bf16_f32 v69, v80, v81
	s_nop 1
	v_mfma_f32_32x32x16_bf16 v[50:65], v[126:129], v[66:69], v[50:65]
	v_add_f32_e32 v126, v180, v179
	v_add_f32_e32 v126, v181, v126
	v_mfma_f32_32x32x16_bf16 v[34:49], v[122:125], v[66:69], v[34:49]
	v_add_f32_e32 v122, v182, v126
	v_add_f32_e32 v70, v70, v122
	v_add_f32_e32 v70, v71, v70
	v_add_f32_e32 v70, v72, v70
	v_add_f32_e32 v70, v73, v70
	v_add_f32_e32 v70, v74, v70
	v_add_f32_e32 v70, v75, v70
	v_mfma_f32_32x32x16_bf16 v[18:33], v[118:121], v[66:69], v[18:33]
	v_add_f32_e32 v70, v76, v70
	v_add_f32_e32 v70, v77, v70
	v_add_f32_e32 v70, v78, v70
	v_add_f32_e32 v70, v79, v70
	v_add_f32_e32 v70, v80, v70
	v_add_f32_e32 v70, v81, v70
	v_add_f32_e32 v175, v175, v70
	v_mfma_f32_32x32x16_bf16 v[2:17], v[114:117], v[66:69], v[2:17]
	s_branch .LBB0_545
.Lp3_sp0:
	v_max_f32_e32 v179, v66, v67
	v_max3_f32 v179, v179, v68, v69
	v_max3_f32 v179, v179, v70, v71
	v_max3_f32 v179, v179, v72, v73
	v_mov_b32_e32 v180, v179
	s_nop 1
	v_permlane32_swap_b32_e32 v180, v179
	v_max_f32_e32 v179, v179, v180
	v_cmp_gt_f32_e32 vcc, v179, v177
	s_cbranch_vccz .Lp3_sp0_nr
	v_max_f32_e32 v179, v179, v179
	v_max_f32_e32 v180, v177, v177
	v_max_f32_e32 v179, v180, v179
	v_sub_f32_e32 v177, v177, v179
	v_exp_f32_e32 v180, v177
	v_mov_b32_e32 v177, v179
	v_pk_mul_f32 v[64:65], v[64:65], v[180:181] op_sel_hi:[1,0]
	v_pk_mul_f32 v[62:63], v[62:63], v[180:181] op_sel_hi:[1,0]
	v_pk_mul_f32 v[60:61], v[60:61], v[180:181] op_sel_hi:[1,0]
	v_pk_mul_f32 v[58:59], v[58:59], v[180:181] op_sel_hi:[1,0]
	v_pk_mul_f32 v[56:57], v[56:57], v[180:181] op_sel_hi:[1,0]
	v_pk_mul_f32 v[54:55], v[54:55], v[180:181] op_sel_hi:[1,0]
	v_pk_mul_f32 v[52:53], v[52:53], v[180:181] op_sel_hi:[1,0]
	v_pk_mul_f32 v[50:51], v[50:51], v[180:181] op_sel_hi:[1,0]
	v_pk_mul_f32 v[48:49], v[48:49], v[180:181] op_sel_hi:[1,0]
	v_pk_mul_f32 v[46:47], v[46:47], v[180:181] op_sel_hi:[1,0]
	v_pk_mul_f32 v[44:45], v[44:45], v[180:181] op_sel_hi:[1,0]
	v_pk_mul_f32 v[42:43], v[42:43], v[180:181] op_sel_hi:[1,0]
	v_pk_mul_f32 v[40:41], v[40:41], v[180:181] op_sel_hi:[1,0]
	v_pk_mul_f32 v[38:39], v[38:39], v[180:181] op_sel_hi:[1,0]
	v_pk_mul_f32 v[36:37], v[36:37], v[180:181] op_sel_hi:[1,0]
	v_pk_mul_f32 v[34:35], v[34:35], v[180:181] op_sel_hi:[1,0]
	v_pk_mul_f32 v[32:33], v[32:33], v[180:181] op_sel_hi:[1,0]
	v_pk_mul_f32 v[30:31], v[30:31], v[180:181] op_sel_hi:[1,0]
	v_pk_mul_f32 v[28:29], v[28:29], v[180:181] op_sel_hi:[1,0]
	v_pk_mul_f32 v[26:27], v[26:27], v[180:181] op_sel_hi:[1,0]
	v_pk_mul_f32 v[24:25], v[24:25], v[180:181] op_sel_hi:[1,0]
	v_pk_mul_f32 v[22:23], v[22:23], v[180:181] op_sel_hi:[1,0]
	v_pk_mul_f32 v[20:21], v[20:21], v[180:181] op_sel_hi:[1,0]
	v_pk_mul_f32 v[18:19], v[18:19], v[180:181] op_sel_hi:[1,0]
	v_pk_mul_f32 v[16:17], v[16:17], v[180:181] op_sel_hi:[1,0]
	v_pk_mul_f32 v[14:15], v[14:15], v[180:181] op_sel_hi:[1,0]
	v_pk_mul_f32 v[12:13], v[12:13], v[180:181] op_sel_hi:[1,0]
	v_pk_mul_f32 v[10:11], v[10:11], v[180:181] op_sel_hi:[1,0]
	v_pk_mul_f32 v[8:9], v[8:9], v[180:181] op_sel_hi:[1,0]
	v_pk_mul_f32 v[6:7], v[6:7], v[180:181] op_sel_hi:[1,0]
	v_pk_mul_f32 v[4:5], v[4:5], v[180:181] op_sel_hi:[1,0]
	v_pk_mul_f32 v[2:3], v[2:3], v[180:181] op_sel_hi:[1,0]
	v_mul_f32_e32 v175, v175, v180
.Lp3_sp0_nr:
	v_sub_f32_e32 v66, v66, v177
	v_sub_f32_e32 v67, v67, v177
	v_sub_f32_e32 v68, v68, v177
	v_sub_f32_e32 v69, v69, v177
	v_sub_f32_e32 v70, v70, v177
	v_sub_f32_e32 v71, v71, v177
	v_sub_f32_e32 v72, v72, v177
	v_sub_f32_e32 v73, v73, v177
	v_exp_f32_e32 v179, v66
	v_exp_f32_e32 v180, v67
	v_exp_f32_e32 v181, v68
	v_exp_f32_e32 v182, v69
	v_exp_f32_e32 v70, v70
	v_exp_f32_e32 v71, v71
	v_exp_f32_e32 v72, v72
	v_exp_f32_e32 v73, v73
	v_cvt_pk_bf16_f32 v66, v179, v180
	v_cvt_pk_bf16_f32 v67, v181, v182
	v_cvt_pk_bf16_f32 v68, v70, v71
	v_cvt_pk_bf16_f32 v69, v72, v73
	s_waitcnt lgkmcnt(0)
	s_nop 1
	v_mfma_f32_32x32x16_bf16 v[50:65], v[142:145], v[66:69], v[50:65]
	v_mfma_f32_32x32x16_bf16 v[34:49], v[138:141], v[66:69], v[34:49]
	v_mfma_f32_32x32x16_bf16 v[18:33], v[134:137], v[66:69], v[18:33]
	v_mfma_f32_32x32x16_bf16 v[2:17], v[130:133], v[66:69], v[2:17]
	v_add_f32_e32 v126, v180, v179
	v_add_f32_e32 v126, v181, v126
	v_add_f32_e32 v122, v182, v126
	v_add_f32_e32 v70, v70, v122
	v_add_f32_e32 v70, v71, v70
	v_add_f32_e32 v70, v72, v70
	v_add_f32_e32 v70, v73, v70
	v_add_f32_e32 v175, v175, v70
	s_branch .LBB0_545
.Lp3_sp1:
	v_max_f32_e32 v179, v74, v75
	v_max3_f32 v179, v179, v76, v77
	v_max3_f32 v179, v179, v78, v79
	v_max3_f32 v179, v179, v80, v81
	v_mov_b32_e32 v180, v179
	s_nop 1
	v_permlane32_swap_b32_e32 v180, v179
	v_max_f32_e32 v179, v179, v180
	v_cmp_gt_f32_e32 vcc, v179, v177
	s_cbranch_vccz .Lp3_sp1_nr
	v_max_f32_e32 v179, v179, v179
	v_max_f32_e32 v180, v177, v177
	v_max_f32_e32 v179, v180, v179
	v_sub_f32_e32 v177, v177, v179
	v_exp_f32_e32 v180, v177
	v_mov_b32_e32 v177, v179
	v_pk_mul_f32 v[64:65], v[64:65], v[180:181] op_sel_hi:[1,0]
	v_pk_mul_f32 v[62:63], v[62:63], v[180:181] op_sel_hi:[1,0]
	v_pk_mul_f32 v[60:61], v[60:61], v[180:181] op_sel_hi:[1,0]
	v_pk_mul_f32 v[58:59], v[58:59], v[180:181] op_sel_hi:[1,0]
	v_pk_mul_f32 v[56:57], v[56:57], v[180:181] op_sel_hi:[1,0]
	v_pk_mul_f32 v[54:55], v[54:55], v[180:181] op_sel_hi:[1,0]
	v_pk_mul_f32 v[52:53], v[52:53], v[180:181] op_sel_hi:[1,0]
	v_pk_mul_f32 v[50:51], v[50:51], v[180:181] op_sel_hi:[1,0]
	v_pk_mul_f32 v[48:49], v[48:49], v[180:181] op_sel_hi:[1,0]
	v_pk_mul_f32 v[46:47], v[46:47], v[180:181] op_sel_hi:[1,0]
	v_pk_mul_f32 v[44:45], v[44:45], v[180:181] op_sel_hi:[1,0]
	v_pk_mul_f32 v[42:43], v[42:43], v[180:181] op_sel_hi:[1,0]
	v_pk_mul_f32 v[40:41], v[40:41], v[180:181] op_sel_hi:[1,0]
	v_pk_mul_f32 v[38:39], v[38:39], v[180:181] op_sel_hi:[1,0]
	v_pk_mul_f32 v[36:37], v[36:37], v[180:181] op_sel_hi:[1,0]
	v_pk_mul_f32 v[34:35], v[34:35], v[180:181] op_sel_hi:[1,0]
	v_pk_mul_f32 v[32:33], v[32:33], v[180:181] op_sel_hi:[1,0]
	v_pk_mul_f32 v[30:31], v[30:31], v[180:181] op_sel_hi:[1,0]
	v_pk_mul_f32 v[28:29], v[28:29], v[180:181] op_sel_hi:[1,0]
	v_pk_mul_f32 v[26:27], v[26:27], v[180:181] op_sel_hi:[1,0]
	v_pk_mul_f32 v[24:25], v[24:25], v[180:181] op_sel_hi:[1,0]
	v_pk_mul_f32 v[22:23], v[22:23], v[180:181] op_sel_hi:[1,0]
	v_pk_mul_f32 v[20:21], v[20:21], v[180:181] op_sel_hi:[1,0]
	v_pk_mul_f32 v[18:19], v[18:19], v[180:181] op_sel_hi:[1,0]
	v_pk_mul_f32 v[16:17], v[16:17], v[180:181] op_sel_hi:[1,0]
	v_pk_mul_f32 v[14:15], v[14:15], v[180:181] op_sel_hi:[1,0]
	v_pk_mul_f32 v[12:13], v[12:13], v[180:181] op_sel_hi:[1,0]
	v_pk_mul_f32 v[10:11], v[10:11], v[180:181] op_sel_hi:[1,0]
	v_pk_mul_f32 v[8:9], v[8:9], v[180:181] op_sel_hi:[1,0]
	v_pk_mul_f32 v[6:7], v[6:7], v[180:181] op_sel_hi:[1,0]
	v_pk_mul_f32 v[4:5], v[4:5], v[180:181] op_sel_hi:[1,0]
	v_pk_mul_f32 v[2:3], v[2:3], v[180:181] op_sel_hi:[1,0]
	v_mul_f32_e32 v175, v175, v180
.Lp3_sp1_nr:
	v_sub_f32_e32 v74, v74, v177
	v_sub_f32_e32 v75, v75, v177
	v_sub_f32_e32 v76, v76, v177
	v_sub_f32_e32 v77, v77, v177
	v_sub_f32_e32 v78, v78, v177
	v_sub_f32_e32 v79, v79, v177
	v_sub_f32_e32 v80, v80, v177
	v_sub_f32_e32 v81, v81, v177
	v_exp_f32_e32 v74, v74
	v_exp_f32_e32 v75, v75
	v_exp_f32_e32 v76, v76
	v_exp_f32_e32 v77, v77
	v_exp_f32_e32 v78, v78
	v_exp_f32_e32 v79, v79
	v_exp_f32_e32 v80, v80
	v_exp_f32_e32 v81, v81
	v_cvt_pk_bf16_f32 v66, v74, v75
	v_cvt_pk_bf16_f32 v67, v76, v77
	v_cvt_pk_bf16_f32 v68, v78, v79
	v_cvt_pk_bf16_f32 v69, v80, v81
	s_waitcnt lgkmcnt(0)
	s_nop 1
	v_mfma_f32_32x32x16_bf16 v[50:65], v[126:129], v[66:69], v[50:65]
	v_mfma_f32_32x32x16_bf16 v[34:49], v[122:125], v[66:69], v[34:49]
	v_mfma_f32_32x32x16_bf16 v[18:33], v[118:121], v[66:69], v[18:33]
	v_mfma_f32_32x32x16_bf16 v[2:17], v[114:117], v[66:69], v[2:17]
	v_add_f32_e32 v70, v75, v74
	v_add_f32_e32 v70, v76, v70
	v_add_f32_e32 v70, v77, v70
	v_add_f32_e32 v70, v78, v70
	v_add_f32_e32 v70, v79, v70
	v_add_f32_e32 v70, v80, v70
	v_add_f32_e32 v70, v81, v70
	v_add_f32_e32 v175, v175, v70
	s_branch .LBB0_545
